# GDN prep S1: conv weight sets prefetched (set 1 at the top of S0 into otherwise unused registers, set 2 where set 1 used to be loaded), loop waits relaxed to vmcnt(8)
# baseline (speedup 1.0000x reference)
.LBB0_44:
	v_ashrrev_i32_e32 v2, 9, v46
	v_ashrrev_i32_e32 v3, 31, v2
	s_waitcnt lgkmcnt(0)
	s_barrier
	v_readlane_b32 s0, v254, 37
	v_and_b32_e32 v0, 63, v46
	v_bfe_u32 v7, v46, 6, 3
	v_lshlrev_b64 v[82:83], 12, v[2:3]
	v_readlane_b32 s1, v254, 38
	v_cmp_eq_u32_e32 vcc, s0, v46
	v_lshl_or_b32 v82, v0, 6, v82
	s_and_b64 s[0:1], s[6:7], vcc
	v_lshlrev_b32_e32 v84, 7, v7
	v_or_b32_e32 v226, v84, v116
	v_lshlrev_b32_e32 v226, 2, v226
	v_add_u32_e32 v227, 0x3000, v226
	v_add_u32_e32 v220, 0x6000, v226
	v_add_u32_e32 v221, 0x9000, v226
	global_load_dwordx4 v[190:193], v226, s[86:87]
	global_load_dwordx4 v[194:197], v226, s[86:87] offset:16
	global_load_dwordx4 v[198:201], v227, s[86:87]
	global_load_dwordx4 v[206:209], v227, s[86:87] offset:16
	global_load_dwordx4 v[210:213], v220, s[86:87]
	global_load_dwordx4 v[214:217], v220, s[86:87] offset:16
	global_load_dwordx4 v[238:241], v221, s[86:87]
	global_load_dwordx4 v[242:245], v221, s[86:87] offset:16
	s_and_saveexec_b64 s[20:21], s[0:1]
	s_cbranch_execz .LBB0_63
	v_lshrrev_b32_e32 v3, 6, v46
	v_and_b32_e32 v3, 7, v3
	v_cmp_ne_u32_e32 vcc, 0, v0
	v_lshl_or_b32 v0, v2, 6, v0
	v_lshl_add_u32 v6, v3, 7, v154
	v_add_u32_e32 v9, 0x700, v84
	v_lshl_add_u32 v14, v0, 1, v0
	s_mov_b64 s[24:25], 0
	v_mov_b32_e32 v15, v155
	v_mov_b32_e32 v8, v166
	s_branch .LBB0_47

.LBB0_65:
	s_or_b64 exec, exec, s[0:1]
	s_waitcnt lgkmcnt(0)
	s_barrier
	s_nop 0
	v_or_b32_e32 v0, v84, v115
	v_lshlrev_b32_e32 v0, 2, v0
	v_lshl_add_u64 v[26:27], s[86:87], 0, v[0:1]
	v_add_co_u32_e32 v2, vcc, 0x2000, v26
	s_mov_b64 s[0:1], 0x5000
	s_nop 0
	v_addc_co_u32_e32 v3, vcc, 0, v27, vcc
	v_add_co_u32_e32 v10, vcc, 0x5000, v26
	v_lshl_add_u64 v[14:15], v[26:27], 0, s[0:1]
	s_nop 0
	v_addc_co_u32_e32 v11, vcc, 0, v27, vcc
	s_mov_b64 s[0:1], 0x8000
	v_add_co_u32_e32 v18, vcc, 0x8000, v26
	v_lshl_add_u64 v[22:23], v[26:27], 0, s[0:1]
	s_nop 0
	v_addc_co_u32_e32 v19, vcc, 0, v27, vcc
	s_mov_b64 s[0:1], 0xb000
	v_lshl_add_u64 v[6:7], v[26:27], 0, s[76:77]
	v_lshl_add_u64 v[30:31], v[26:27], 0, s[0:1]
	v_add_co_u32_e32 v26, vcc, 0xb000, v26
	global_load_dwordx4 v[2:5], v[2:3], off
	s_nop 0
	global_load_dwordx4 v[6:9], v[6:7], off offset:16
	v_addc_co_u32_e32 v27, vcc, 0, v27, vcc
	global_load_dwordx4 v[10:13], v[10:11], off
	s_nop 0
	global_load_dwordx4 v[14:17], v[14:15], off offset:16
	s_nop 0
	global_load_dwordx4 v[18:21], v[18:19], off
	s_nop 0
	global_load_dwordx4 v[22:25], v[22:23], off offset:16
	s_nop 0
	global_load_dwordx4 v[26:29], v[26:27], off
	s_nop 0
	global_load_dwordx4 v[30:33], v[30:31], off offset:16
	s_mov_b32 s18, 0
	v_mov_b32_e32 v0, v157
.LBB0_66:
	ds_read_b128 v[34:37], v0
	ds_read_b128 v[86:89], v0 offset:768
	ds_read_b128 v[90:93], v0 offset:1536
	ds_read_b128 v[94:97], v0 offset:2304
	v_add_u32_e32 v0, 0x3000, v0
	s_waitcnt lgkmcnt(0)
	v_lshlrev_b32_e32 v98, 16, v37
	v_and_b32_e32 v99, 0xffff0000, v37
	s_waitcnt vmcnt(8)
	v_pk_fma_f32 v[98:99], v[196:197], v[98:99], 0 op_sel_hi:[1,1,0]
	s_waitcnt lgkmcnt(2)
	v_lshlrev_b32_e32 v100, 16, v89
	v_and_b32_e32 v101, 0xffff0000, v89
	s_waitcnt vmcnt(8)
	v_pk_fma_f32 v[98:99], v[208:209], v[100:101], v[98:99]
	s_waitcnt lgkmcnt(1)
	v_lshlrev_b32_e32 v100, 16, v93
	v_and_b32_e32 v101, 0xffff0000, v93
	s_waitcnt vmcnt(8)
	v_pk_fma_f32 v[98:99], v[216:217], v[100:101], v[98:99]
	s_waitcnt lgkmcnt(0)
	v_lshlrev_b32_e32 v100, 16, v97
	v_and_b32_e32 v101, 0xffff0000, v97
	s_waitcnt vmcnt(8)
	v_pk_fma_f32 v[98:99], v[244:245], v[100:101], v[98:99]
	v_and_b32_e32 v89, 0xffff0000, v92
	v_mul_f32_e32 v37, 0xbfb8aa3b, v98
	v_exp_f32_e32 v37, v37
	v_and_b32_e32 v97, 0xffff0000, v87
	v_add_f32_e32 v37, 1.0, v37
	v_rcp_f32_e32 v100, v37
	v_mul_f32_e32 v37, 0xbfb8aa3b, v99
	v_exp_f32_e32 v37, v37
	s_nop 0
	v_add_f32_e32 v37, 1.0, v37
	v_rcp_f32_e32 v101, v37
	s_nop 0
	v_pk_mul_f32 v[98:99], v[98:99], v[100:101]
	v_lshlrev_b32_e32 v100, 16, v36
	v_and_b32_e32 v101, 0xffff0000, v36
	v_pk_fma_f32 v[36:37], v[194:195], v[100:101], 0 op_sel_hi:[1,1,0]
	v_lshlrev_b32_e32 v100, 16, v88
	v_and_b32_e32 v101, 0xffff0000, v88
	v_pk_fma_f32 v[36:37], v[206:207], v[100:101], v[36:37]
	v_lshlrev_b32_e32 v88, 16, v92
	v_pk_fma_f32 v[36:37], v[214:215], v[88:89], v[36:37]
	v_lshlrev_b32_e32 v88, 16, v96
	v_and_b32_e32 v89, 0xffff0000, v96
	v_pk_fma_f32 v[36:37], v[242:243], v[88:89], v[36:37]
	v_mov_b32_e32 v92, v99
	v_mul_f32_e32 v47, 0xbfb8aa3b, v36
	v_exp_f32_e32 v47, v47
	v_lshlrev_b32_e32 v96, 16, v87
	v_and_b32_e32 v87, 0xffff0000, v90
	v_add_f32_e32 v47, 1.0, v47
	v_rcp_f32_e32 v88, v47
	v_mul_f32_e32 v47, 0xbfb8aa3b, v37
	v_exp_f32_e32 v47, v47
	s_nop 0
	v_add_f32_e32 v47, 1.0, v47
	v_rcp_f32_e32 v89, v47
	s_nop 0
	v_pk_mul_f32 v[36:37], v[36:37], v[88:89]
	s_nop 0
	v_mov_b32_e32 v93, v37
	v_mov_b32_e32 v88, v98
	v_mov_b32_e32 v89, v36
	v_pk_mul_f32 v[92:93], v[92:93], v[92:93]
	s_nop 0
	v_pk_fma_f32 v[88:89], v[88:89], v[88:89], v[92:93]
	v_lshlrev_b32_e32 v92, 16, v35
	v_and_b32_e32 v93, 0xffff0000, v35
	v_pk_fma_f32 v[92:93], v[192:193], v[92:93], 0 op_sel_hi:[1,1,0]
	s_nop 0
	v_pk_fma_f32 v[92:93], v[200:201], v[96:97], v[92:93]
	v_lshlrev_b32_e32 v96, 16, v91
	v_and_b32_e32 v97, 0xffff0000, v91
	v_pk_fma_f32 v[92:93], v[212:213], v[96:97], v[92:93]
	v_lshlrev_b32_e32 v96, 16, v95
	v_and_b32_e32 v97, 0xffff0000, v95
	v_pk_fma_f32 v[92:93], v[240:241], v[96:97], v[92:93]
	s_nop 0
	v_mul_f32_e32 v35, 0xbfb8aa3b, v92
	v_exp_f32_e32 v35, v35
	s_nop 0
	v_add_f32_e32 v35, 1.0, v35
	v_rcp_f32_e32 v96, v35
	v_mul_f32_e32 v35, 0xbfb8aa3b, v93
	v_exp_f32_e32 v35, v35
	s_nop 0
	v_add_f32_e32 v35, 1.0, v35
	v_rcp_f32_e32 v97, v35
	s_nop 0
	v_pk_mul_f32 v[92:93], v[92:93], v[96:97]
	v_lshlrev_b32_e32 v96, 16, v34
	v_and_b32_e32 v97, 0xffff0000, v34
	v_pk_fma_f32 v[34:35], v[190:191], v[96:97], 0 op_sel_hi:[1,1,0]
	v_lshlrev_b32_e32 v96, 16, v86
	v_and_b32_e32 v97, 0xffff0000, v86
	v_pk_fma_f32 v[34:35], v[198:199], v[96:97], v[34:35]
	v_lshlrev_b32_e32 v86, 16, v90
	v_pk_fma_f32 v[34:35], v[210:211], v[86:87], v[34:35]
	v_lshlrev_b32_e32 v86, 16, v94
	v_and_b32_e32 v87, 0xffff0000, v94
	v_pk_fma_f32 v[34:35], v[238:239], v[86:87], v[34:35]
	v_mov_b32_e32 v91, v93
	v_mul_f32_e32 v47, 0xbfb8aa3b, v34
	v_exp_f32_e32 v47, v47
	s_nop 0
	v_add_f32_e32 v47, 1.0, v47
	v_rcp_f32_e32 v86, v47
	v_mul_f32_e32 v47, 0xbfb8aa3b, v35
	v_exp_f32_e32 v47, v47
	s_nop 0
	v_add_f32_e32 v47, 1.0, v47
	v_rcp_f32_e32 v87, v47
	s_nop 0
	v_pk_mul_f32 v[34:35], v[34:35], v[86:87]
	s_nop 0
	v_mov_b32_e32 v90, v35
	v_mov_b32_e32 v86, v34
	v_mov_b32_e32 v87, v92
	v_pk_mul_f32 v[90:91], v[90:91], v[90:91]
	s_nop 0
	v_pk_fma_f32 v[86:87], v[86:87], v[86:87], v[90:91]
	s_nop 0
	v_add_f32_e32 v47, v86, v87
	v_add_f32_e32 v47, v89, v47
	v_add_f32_e32 v47, v88, v47
	s_nop 1
	v_add_f32_dpp v47, v47, v47 row_ror:8 row_mask:0xf bank_mask:0xf bound_ctrl:1
	s_nop 1
	v_add_f32_dpp v47, v47, v47 row_ror:4 row_mask:0xf bank_mask:0xf bound_ctrl:1
	s_nop 1
	v_add_f32_dpp v47, v47, v47 row_ror:2 row_mask:0xf bank_mask:0xf bound_ctrl:1
	s_nop 1
	v_add_f32_dpp v47, v47, v47 row_ror:1 row_mask:0xf bank_mask:0xf bound_ctrl:1
	v_add_f32_e32 v47, 0x358637bd, v47
	v_cmp_gt_f32_e32 vcc, s79, v47
	v_mul_f32_e32 v49, 0x4f800000, v47
	s_nop 0
	v_cndmask_b32_e32 v47, v47, v49, vcc
	v_sqrt_f32_e32 v49, v47
	s_nop 0
	v_add_u32_e32 v51, -1, v49
	v_fma_f32 v53, -v51, v49, v47
	v_cmp_ge_f32_e64 s[0:1], 0, v53
	v_add_u32_e32 v53, 1, v49
	s_nop 0
	v_cndmask_b32_e64 v51, v49, v51, s[0:1]
	v_fma_f32 v49, -v53, v49, v47
	v_cmp_lt_f32_e64 s[0:1], 0, v49
	s_nop 1
	v_cndmask_b32_e64 v49, v51, v53, s[0:1]
	v_mul_f32_e32 v51, 0x37800000, v49
	v_cndmask_b32_e32 v49, v49, v51, vcc
	v_cmp_class_f32_e32 vcc, v47, v205
	s_nop 1
	v_cndmask_b32_e32 v47, v49, v47, vcc
	v_div_scale_f32 v49, s[0:1], v47, v47, 1.0
	v_rcp_f32_e32 v51, v49
	s_nop 0
	v_fma_f32 v53, -v49, v51, 1.0
	v_fmac_f32_e32 v51, v53, v51
	v_div_scale_f32 v53, vcc, 1.0, v47, 1.0
	v_mul_f32_e32 v55, v53, v51
	v_fma_f32 v57, -v49, v55, v53
	v_fmac_f32_e32 v55, v57, v51
	v_fma_f32 v49, -v49, v55, v53
	v_div_fmas_f32 v49, v49, v51, v55
	v_div_fixup_f32 v47, v49, v47, 1.0
	v_mul_f32_e32 v86, v117, v47
	v_pk_mul_f32 v[34:35], v[34:35], v[86:87] op_sel_hi:[1,0]
	v_pk_mul_f32 v[88:89], v[92:93], v[86:87] op_sel_hi:[1,0]
	v_pk_mul_f32 v[36:37], v[36:37], v[86:87] op_sel_hi:[1,0]
	v_pk_mul_f32 v[86:87], v[98:99], v[86:87] op_sel_hi:[1,0]
	v_add_u32_e32 v47, s18, v156
	s_addk_i32 s18, 0x1100
	v_cvt_pk_bf16_f32 v34, v34, v35
	v_cvt_pk_bf16_f32 v35, v88, v89
	v_cvt_pk_bf16_f32 v36, v36, v37
	v_cvt_pk_bf16_f32 v37, v86, v87
	s_cmpk_eq_i32 s18, 0x4400
	ds_write_b128 v47, v[34:37]
	s_cbranch_scc0 .LBB0_66
	s_mov_b32 s18, 0
	s_mov_b64 s[0:1], -1
